# nt (non-temporal) hint on the stores of all four GEMM epilogues (w_in, w_out, MLP1, MLP2): write-once intermediates no longer displace the weight/activation tiles in L2
# speedup vs baseline: 1.0155x; 1.0000x over previous
; __device__ __forceinline__ unsigned pk2(float lo, float hi) { const v2f_t f = {lo, hi}; const v2bf_t b = __builtin_convertvector(f, v2bf_t); return __builtin_bit_cast(unsigned, b); }
;     __device__ __forceinline__ void operator()(const f32x4 (&acc)[2][2][4][2], const Unit& u, int wr, int wc, int fr, int fq) const {
;     ...
;             const int col0 = colt + wc * 32 + 8 * fq;
; #pragma unroll
;             for (int ai = 0; ai < 2; ++ai)
; #pragma unroll
;                 for (int m = 0; m < 4; ++m) { bf16_t* rowp = base + (size_t)(row0 + ai * 128 + m * 16) * ld + col0;
; #pragma unroll
;                     for (int bj = 0; bj < 2; ++bj) { const f32x4 v0 = acc[ai][bj][m][0], v1 = acc[ai][bj][m][1];
;                         u32x4 w; w.x = pk2(v0[0], v0[1]); w.y = pk2(v0[2], v0[3]); w.z = pk2(v1[0], v1[1]); w.w = pk2(v1[2], v1[3]);
;                         *(u32x4*)(rowp + bj * 128) = w; } }
.LBB0_255:
	v_and_b32_e32 v157, 15, v194
	v_bfe_u32 v158, v194, 6, 2
	v_bfe_u32 v159, v194, 4, 2
	v_bfe_u32 v156, v194, 8, 1
	v_lshlrev_b32_e32 v156, 4, v156
	v_add_u32_e32 v156, v156, v157
	v_mul_u32_u24_e32 v186, 0x110, v156
	v_lshl_add_u32 v186, v158, 6, v186
	v_lshl_add_u32 v186, v159, 4, v186
	v_add_u32_e32 v186, 0x23410, v186
	v_lshrrev_b32_e32 v160, 6, v194
	v_lshl_add_u32 v160, v160, 2, v159
	v_mul_u32_u24_e32 v187, 0x110, v160
	v_lshl_add_u32 v187, v157, 4, v187
	v_add_u32_e32 v187, 0x23410, v187
	v_sub_u32_e32 v156, v142, v157
	v_lshl_add_u32 v156, v158, 2, v156
	v_add_u32_e32 v156, v156, v159
	v_mul_lo_u32 v156, v156, s48
	v_lshlrev_b32_e32 v156, 1, v156
	v_lshlrev_b32_e32 v160, 4, v157
	v_lshl_add_u32 v160, s39, 1, v160
	v_add_u32_e32 v156, v156, v160
	v_mov_b32_e32 v157, 0
	v_lshl_add_u64 v[188:189], s[50:51], 0, v[156:157]
	s_mov_b32 s99, 0
	v_cvt_pk_bf16_f32 v174, v126, v127
	v_cvt_pk_bf16_f32 v175, v128, v129
	v_cvt_pk_bf16_f32 v176, v122, v123
	v_cvt_pk_bf16_f32 v177, v124, v125
	ds_write_b128 v186, v[174:177]
	s_waitcnt lgkmcnt(0)
	s_barrier
	ds_read_b128 v[178:181], v187
	s_mul_i32 s98, s48, 0
	v_lshl_add_u64 v[190:191], v[188:189], 0, s[98:99]
	v_cvt_pk_bf16_f32 v174, v118, v119
	v_cvt_pk_bf16_f32 v175, v120, v121
	v_cvt_pk_bf16_f32 v176, v114, v115
	v_cvt_pk_bf16_f32 v177, v116, v117
	ds_write_b128 v186, v[174:177] offset:8704
	s_waitcnt lgkmcnt(1)
	global_store_dwordx4 v[190:191], v[178:181], off nt
	s_waitcnt lgkmcnt(0)
	s_barrier
	ds_read_b128 v[182:185], v187 offset:8704
	v_cvt_pk_bf16_f32 v174, v110, v111
	v_cvt_pk_bf16_f32 v175, v112, v113
	v_cvt_pk_bf16_f32 v176, v106, v107
	v_cvt_pk_bf16_f32 v177, v108, v109
	ds_write_b128 v186, v[174:177]
	s_waitcnt lgkmcnt(1)
	global_store_dwordx4 v[190:191], v[182:185], off offset:256 nt
	s_waitcnt lgkmcnt(0)
	s_barrier
	ds_read_b128 v[178:181], v187
	s_mul_i32 s98, s48, 32
	v_lshl_add_u64 v[190:191], v[188:189], 0, s[98:99]
	v_cvt_pk_bf16_f32 v174, v102, v103
	v_cvt_pk_bf16_f32 v175, v104, v105
	v_cvt_pk_bf16_f32 v176, v98, v99
	v_cvt_pk_bf16_f32 v177, v100, v101
	ds_write_b128 v186, v[174:177] offset:8704
	s_waitcnt lgkmcnt(1)
	global_store_dwordx4 v[190:191], v[178:181], off nt
	s_waitcnt lgkmcnt(0)
	s_barrier
	ds_read_b128 v[182:185], v187 offset:8704
	v_cvt_pk_bf16_f32 v174, v94, v95
	v_cvt_pk_bf16_f32 v175, v96, v97
	v_cvt_pk_bf16_f32 v176, v90, v91
	v_cvt_pk_bf16_f32 v177, v92, v93
	ds_write_b128 v186, v[174:177]
	s_waitcnt lgkmcnt(1)
	global_store_dwordx4 v[190:191], v[182:185], off offset:256 nt
	s_waitcnt lgkmcnt(0)
	s_barrier
	ds_read_b128 v[178:181], v187
	s_mul_i32 s98, s48, 64
	v_lshl_add_u64 v[190:191], v[188:189], 0, s[98:99]
	v_cvt_pk_bf16_f32 v174, v86, v87
	v_cvt_pk_bf16_f32 v175, v88, v89
	v_cvt_pk_bf16_f32 v176, v82, v83
	v_cvt_pk_bf16_f32 v177, v84, v85
	ds_write_b128 v186, v[174:177] offset:8704
	s_waitcnt lgkmcnt(1)
	global_store_dwordx4 v[190:191], v[178:181], off nt
	s_waitcnt lgkmcnt(0)
	s_barrier
	ds_read_b128 v[182:185], v187 offset:8704
	v_cvt_pk_bf16_f32 v174, v78, v79
	v_cvt_pk_bf16_f32 v175, v80, v81
	v_cvt_pk_bf16_f32 v176, v74, v75
	v_cvt_pk_bf16_f32 v177, v76, v77
	ds_write_b128 v186, v[174:177]
	s_waitcnt lgkmcnt(1)
	global_store_dwordx4 v[190:191], v[182:185], off offset:256 nt
	s_waitcnt lgkmcnt(0)
	s_barrier
	ds_read_b128 v[178:181], v187
	s_mul_i32 s98, s48, 96
	v_lshl_add_u64 v[190:191], v[188:189], 0, s[98:99]
	v_cvt_pk_bf16_f32 v174, v70, v71
	v_cvt_pk_bf16_f32 v175, v72, v73
	v_cvt_pk_bf16_f32 v176, v66, v67
	v_cvt_pk_bf16_f32 v177, v68, v69
	ds_write_b128 v186, v[174:177] offset:8704
	s_waitcnt lgkmcnt(1)
	global_store_dwordx4 v[190:191], v[178:181], off nt
	s_waitcnt lgkmcnt(0)
	s_barrier
	ds_read_b128 v[182:185], v187 offset:8704
	v_cvt_pk_bf16_f32 v174, v60, v61
	v_cvt_pk_bf16_f32 v175, v62, v63
	v_cvt_pk_bf16_f32 v176, v56, v57
	v_cvt_pk_bf16_f32 v177, v58, v59
	ds_write_b128 v186, v[174:177]
	s_waitcnt lgkmcnt(1)
	global_store_dwordx4 v[190:191], v[182:185], off offset:256 nt
	s_waitcnt lgkmcnt(0)
	s_barrier
	ds_read_b128 v[178:181], v187
	s_mul_i32 s98, s48, 256
	v_lshl_add_u64 v[190:191], v[188:189], 0, s[98:99]
	v_cvt_pk_bf16_f32 v174, v52, v53
	v_cvt_pk_bf16_f32 v175, v54, v55
	v_cvt_pk_bf16_f32 v176, v48, v49
	v_cvt_pk_bf16_f32 v177, v50, v51
	ds_write_b128 v186, v[174:177] offset:8704
	s_waitcnt lgkmcnt(1)
	global_store_dwordx4 v[190:191], v[178:181], off nt
	s_waitcnt lgkmcnt(0)
	s_barrier
	ds_read_b128 v[182:185], v187 offset:8704
	v_cvt_pk_bf16_f32 v174, v44, v45
	v_cvt_pk_bf16_f32 v175, v46, v47
	v_cvt_pk_bf16_f32 v176, v40, v41
	v_cvt_pk_bf16_f32 v177, v42, v43
	ds_write_b128 v186, v[174:177]
	s_waitcnt lgkmcnt(1)
	global_store_dwordx4 v[190:191], v[182:185], off offset:256 nt
	s_waitcnt lgkmcnt(0)
	s_barrier
	ds_read_b128 v[178:181], v187
	s_mul_i32 s98, s48, 288
	v_lshl_add_u64 v[190:191], v[188:189], 0, s[98:99]
	v_cvt_pk_bf16_f32 v174, v36, v37
	v_cvt_pk_bf16_f32 v175, v38, v39
	v_cvt_pk_bf16_f32 v176, v32, v33
	v_cvt_pk_bf16_f32 v177, v34, v35
	ds_write_b128 v186, v[174:177] offset:8704
	s_waitcnt lgkmcnt(1)
	global_store_dwordx4 v[190:191], v[178:181], off nt
	s_waitcnt lgkmcnt(0)
	s_barrier
	ds_read_b128 v[182:185], v187 offset:8704
	v_cvt_pk_bf16_f32 v174, v28, v29
	v_cvt_pk_bf16_f32 v175, v30, v31
	v_cvt_pk_bf16_f32 v176, v24, v25
	v_cvt_pk_bf16_f32 v177, v26, v27
	ds_write_b128 v186, v[174:177]
	s_waitcnt lgkmcnt(1)
	global_store_dwordx4 v[190:191], v[182:185], off offset:256 nt
	s_waitcnt lgkmcnt(0)
	s_barrier
	ds_read_b128 v[178:181], v187
	s_mul_i32 s98, s48, 320
	v_lshl_add_u64 v[190:191], v[188:189], 0, s[98:99]
	v_cvt_pk_bf16_f32 v174, v20, v21
	v_cvt_pk_bf16_f32 v175, v22, v23
	v_cvt_pk_bf16_f32 v176, v16, v17
	v_cvt_pk_bf16_f32 v177, v18, v19
	ds_write_b128 v186, v[174:177] offset:8704
	s_waitcnt lgkmcnt(1)
	global_store_dwordx4 v[190:191], v[178:181], off nt
	s_waitcnt lgkmcnt(0)
	s_barrier
	ds_read_b128 v[182:185], v187 offset:8704
	v_cvt_pk_bf16_f32 v174, v12, v13
	v_cvt_pk_bf16_f32 v175, v14, v15
	v_cvt_pk_bf16_f32 v176, v8, v9
	v_cvt_pk_bf16_f32 v177, v10, v11
	ds_write_b128 v186, v[174:177]
	s_waitcnt lgkmcnt(1)
	global_store_dwordx4 v[190:191], v[182:185], off offset:256 nt
	s_waitcnt lgkmcnt(0)
	s_barrier
	ds_read_b128 v[178:181], v187
	s_mul_i32 s98, s48, 352
	v_lshl_add_u64 v[190:191], v[188:189], 0, s[98:99]
	v_cvt_pk_bf16_f32 v174, v4, v5
	v_cvt_pk_bf16_f32 v175, v6, v7
	v_cvt_pk_bf16_f32 v176, v0, v1
	v_cvt_pk_bf16_f32 v177, v2, v3
	ds_write_b128 v186, v[174:177] offset:8704
	s_waitcnt lgkmcnt(1)
	global_store_dwordx4 v[190:191], v[178:181], off nt
	s_waitcnt lgkmcnt(0)
	s_barrier
	ds_read_b128 v[182:185], v187 offset:8704
	s_waitcnt lgkmcnt(0)
	global_store_dwordx4 v[190:191], v[182:185], off offset:256 nt

; __device__ __forceinline__ unsigned pk2(float lo, float hi) { const v2f_t f = {lo, hi}; const v2bf_t b = __builtin_convertvector(f, v2bf_t); return __builtin_bit_cast(unsigned, b); }
;     __device__ __forceinline__ void operator()(const f32x4 (&acc)[2][2][4][2], const Unit& u, int wr, int wc, int fr, int fq) const {
;     ...
;         const int mr = u.pm < 64 ? (u.pm >> 4) : 4;
;         const float* gp = gate + (size_t)mr * 6 * D + col0;
;         f32x4 gv[2][2], bv[2][2];
; #pragma unroll
;         for (int bj = 0; bj < 2; ++bj)
; #pragma unroll
;             for (int n = 0; n < 2; ++n) { gv[bj][n] = *(const f32x4*)(gp + bj * 128 + 4 * n); bv[bj][n] = bias ? *(const f32x4*)(bias + col0 + bj * 128 + 4 * n) : (f32x4){0.f, 0.f, 0.f, 0.f}; }
; #pragma unroll
;         for (int ai = 0; ai < 2; ++ai)
; #pragma unroll
;             for (int m = 0; m < 4; ++m) { bf16_t* rowp = delta + (size_t)(row0 + ai * 128 + m * 16) * D + col0;
; #pragma unroll
;                 for (int bj = 0; bj < 2; ++bj) { const f32x4 v0 = gv[bj][0] * (acc[ai][bj][m][0] + bv[bj][0]), v1 = gv[bj][1] * (acc[ai][bj][m][1] + bv[bj][1]);
;                     u32x4 w; w.x = pk2(v0[0], v0[1]); w.y = pk2(v0[2], v0[3]); w.z = pk2(v1[0], v1[1]); w.w = pk2(v1[2], v1[3]);
;                     *(u32x4*)(rowp + bj * 128) = w; } }
.LBB0_696:
	v_lshl_or_b32 v156, s24, 8, v176
	v_lshl_add_u32 v158, s22, 8, v174
	s_cmp_lt_i32 s72, 0
	v_ashrrev_i32_e32 v157, 31, v156
	s_mov_b64 s[24:25], -1
	s_cbranch_scc0 .LBB0_698
	s_ashr_i32 s11, s22, 4
	s_mul_i32 s24, s11, 6
	s_ashr_i32 s25, s24, 31
	s_lshl_b64 s[24:25], s[24:25], 11
	s_cmp_lt_i32 s22, 64
	s_cselect_b32 s25, s25, 0
	s_cselect_b32 s24, s24, 0xc000
	s_lshl_b64 s[24:25], s[24:25], 2
	s_add_u32 s24, s48, s24
	s_addc_u32 s25, s49, s25
	v_and_b32_e32 v157, 15, v194
	v_bfe_u32 v170, v194, 6, 2
	v_bfe_u32 v171, v194, 4, 2
	v_bfe_u32 v172, v194, 8, 1
	v_lshlrev_b32_e32 v172, 4, v172
	v_add_u32_e32 v172, v172, v157
	v_mul_u32_u24_e32 v190, 0x110, v172
	v_lshl_add_u32 v190, v170, 6, v190
	v_lshl_add_u32 v190, v171, 4, v190
	v_add_u32_e32 v190, 0x23410, v190
	v_lshrrev_b32_e32 v172, 6, v194
	v_lshl_add_u32 v172, v172, 2, v171
	v_mul_u32_u24_e32 v191, 0x110, v172
	v_lshl_add_u32 v191, v157, 4, v191
	v_add_u32_e32 v191, 0x23410, v191
	v_sub_u32_e32 v172, v158, v157
	v_lshl_add_u32 v172, v170, 2, v172
	v_add_u32_e32 v172, v172, v171
	v_lshlrev_b32_e32 v172, 12, v172
	v_and_b32_e32 v173, 0xffffff00, v156
	v_lshlrev_b32_e32 v173, 1, v173
	v_lshl_add_u32 v173, v157, 4, v173
	v_add_u32_e32 v172, v172, v173
	v_mov_b32_e32 v173, 0
	v_lshl_add_u64 v[204:205], s[2:3], 0, v[172:173]
	s_mov_b32 s25, 0
	s_waitcnt vmcnt(6)
	v_pk_add_f32 v[126:127], v[126:127], 0 op_sel_hi:[1,0]
	v_pk_add_f32 v[128:129], v[128:129], 0 op_sel_hi:[1,0]
	v_pk_mul_f32 v[126:127], v[126:127], v[240:241]
	v_pk_mul_f32 v[128:129], v[128:129], v[242:243]
	v_pk_add_f32 v[122:123], v[122:123], 0 op_sel_hi:[1,0]
	v_pk_add_f32 v[124:125], v[124:125], 0 op_sel_hi:[1,0]
	v_pk_mul_f32 v[122:123], v[122:123], v[244:245]
	v_pk_mul_f32 v[124:125], v[124:125], v[246:247]
	v_cvt_pk_bf16_f32 v178, v126, v127
	v_cvt_pk_bf16_f32 v179, v128, v129
	v_cvt_pk_bf16_f32 v180, v122, v123
	v_cvt_pk_bf16_f32 v181, v124, v125
	ds_write_b128 v190, v[178:181]
	s_waitcnt lgkmcnt(0)
	s_barrier
	ds_read_b128 v[182:185], v191
	s_mov_b32 s24, 0x0
	v_lshl_add_u64 v[206:207], v[204:205], 0, s[24:25]
	v_pk_add_f32 v[118:119], v[118:119], 0 op_sel_hi:[1,0]
	v_pk_add_f32 v[120:121], v[120:121], 0 op_sel_hi:[1,0]
	v_pk_mul_f32 v[118:119], v[118:119], v[248:249]
	v_pk_mul_f32 v[120:121], v[120:121], v[250:251]
	v_pk_add_f32 v[114:115], v[114:115], 0 op_sel_hi:[1,0]
	v_pk_add_f32 v[116:117], v[116:117], 0 op_sel_hi:[1,0]
	v_pk_mul_f32 v[114:115], v[114:115], v[252:253]
	v_pk_mul_f32 v[116:117], v[116:117], v[254:255]
	v_cvt_pk_bf16_f32 v178, v118, v119
	v_cvt_pk_bf16_f32 v179, v120, v121
	v_cvt_pk_bf16_f32 v180, v114, v115
	v_cvt_pk_bf16_f32 v181, v116, v117
	ds_write_b128 v190, v[178:181] offset:8704
	s_waitcnt lgkmcnt(1)
	global_store_dwordx4 v[206:207], v[182:185], off nt
	s_waitcnt lgkmcnt(0)
	s_barrier
	ds_read_b128 v[186:189], v191 offset:8704
	v_pk_add_f32 v[110:111], v[110:111], 0 op_sel_hi:[1,0]
	v_pk_add_f32 v[112:113], v[112:113], 0 op_sel_hi:[1,0]
	v_pk_mul_f32 v[110:111], v[110:111], v[240:241]
	v_pk_mul_f32 v[112:113], v[112:113], v[242:243]
	v_pk_add_f32 v[106:107], v[106:107], 0 op_sel_hi:[1,0]
	v_pk_add_f32 v[108:109], v[108:109], 0 op_sel_hi:[1,0]
	v_pk_mul_f32 v[106:107], v[106:107], v[244:245]
	v_pk_mul_f32 v[108:109], v[108:109], v[246:247]
	v_cvt_pk_bf16_f32 v178, v110, v111
	v_cvt_pk_bf16_f32 v179, v112, v113
	v_cvt_pk_bf16_f32 v180, v106, v107
	v_cvt_pk_bf16_f32 v181, v108, v109
	ds_write_b128 v190, v[178:181]
	s_waitcnt lgkmcnt(1)
	global_store_dwordx4 v[206:207], v[186:189], off offset:256 nt
	s_waitcnt lgkmcnt(0)
	s_barrier
	ds_read_b128 v[182:185], v191
	s_mov_b32 s24, 0x10000
	v_lshl_add_u64 v[206:207], v[204:205], 0, s[24:25]
	v_pk_add_f32 v[102:103], v[102:103], 0 op_sel_hi:[1,0]
	v_pk_add_f32 v[104:105], v[104:105], 0 op_sel_hi:[1,0]
	v_pk_mul_f32 v[102:103], v[102:103], v[248:249]
	v_pk_mul_f32 v[104:105], v[104:105], v[250:251]
	v_pk_add_f32 v[98:99], v[98:99], 0 op_sel_hi:[1,0]
	v_pk_add_f32 v[100:101], v[100:101], 0 op_sel_hi:[1,0]
	v_pk_mul_f32 v[98:99], v[98:99], v[252:253]
	v_pk_mul_f32 v[100:101], v[100:101], v[254:255]
	v_cvt_pk_bf16_f32 v178, v102, v103
	v_cvt_pk_bf16_f32 v179, v104, v105
	v_cvt_pk_bf16_f32 v180, v98, v99
	v_cvt_pk_bf16_f32 v181, v100, v101
	ds_write_b128 v190, v[178:181] offset:8704
	s_waitcnt lgkmcnt(1)
	global_store_dwordx4 v[206:207], v[182:185], off nt
	s_waitcnt lgkmcnt(0)
	s_barrier
	ds_read_b128 v[186:189], v191 offset:8704
	v_pk_add_f32 v[94:95], v[94:95], 0 op_sel_hi:[1,0]
	v_pk_add_f32 v[96:97], v[96:97], 0 op_sel_hi:[1,0]
	v_pk_mul_f32 v[94:95], v[94:95], v[240:241]
	v_pk_mul_f32 v[96:97], v[96:97], v[242:243]
	v_pk_add_f32 v[90:91], v[90:91], 0 op_sel_hi:[1,0]
	v_pk_add_f32 v[92:93], v[92:93], 0 op_sel_hi:[1,0]
	v_pk_mul_f32 v[90:91], v[90:91], v[244:245]
	v_pk_mul_f32 v[92:93], v[92:93], v[246:247]
	v_cvt_pk_bf16_f32 v178, v94, v95
	v_cvt_pk_bf16_f32 v179, v96, v97
	v_cvt_pk_bf16_f32 v180, v90, v91
	v_cvt_pk_bf16_f32 v181, v92, v93
	ds_write_b128 v190, v[178:181]
	s_waitcnt lgkmcnt(1)
	global_store_dwordx4 v[206:207], v[186:189], off offset:256 nt
	s_waitcnt lgkmcnt(0)
	s_barrier
	ds_read_b128 v[182:185], v191
	s_mov_b32 s24, 0x20000
	v_lshl_add_u64 v[206:207], v[204:205], 0, s[24:25]
	v_pk_add_f32 v[86:87], v[86:87], 0 op_sel_hi:[1,0]
	v_pk_add_f32 v[88:89], v[88:89], 0 op_sel_hi:[1,0]
	v_pk_mul_f32 v[86:87], v[86:87], v[248:249]
	v_pk_mul_f32 v[88:89], v[88:89], v[250:251]
	v_pk_add_f32 v[82:83], v[82:83], 0 op_sel_hi:[1,0]
	v_pk_add_f32 v[84:85], v[84:85], 0 op_sel_hi:[1,0]
	v_pk_mul_f32 v[82:83], v[82:83], v[252:253]
	v_pk_mul_f32 v[84:85], v[84:85], v[254:255]
	v_cvt_pk_bf16_f32 v178, v86, v87
	v_cvt_pk_bf16_f32 v179, v88, v89
	v_cvt_pk_bf16_f32 v180, v82, v83
	v_cvt_pk_bf16_f32 v181, v84, v85
	ds_write_b128 v190, v[178:181] offset:8704
	s_waitcnt lgkmcnt(1)
	global_store_dwordx4 v[206:207], v[182:185], off nt
	s_waitcnt lgkmcnt(0)
	s_barrier
; __device__ __forceinline__ unsigned pk2(float lo, float hi) { const v2f_t f = {lo, hi}; const v2bf_t b = __builtin_convertvector(f, v2bf_t); return __builtin_bit_cast(unsigned, b); }
;     __device__ __forceinline__ void operator()(const f32x4 (&acc)[2][2][4][2], const Unit& u, int wr, int wc, int fr, int fq) const {
;     ...
;         for (int ai = 0; ai < 2; ++ai)
; #pragma unroll
;             for (int m = 0; m < 4; ++m) { bf16_t* rowp = delta + (size_t)(row0 + ai * 128 + m * 16) * D + col0;
; #pragma unroll
;                 for (int bj = 0; bj < 2; ++bj) { const f32x4 v0 = gv[bj][0] * (acc[ai][bj][m][0] + bv[bj][0]), v1 = gv[bj][1] * (acc[ai][bj][m][1] + bv[bj][1]);
;                     u32x4 w; w.x = pk2(v0[0], v0[1]); w.y = pk2(v0[2], v0[3]); w.z = pk2(v1[0], v1[1]); w.w = pk2(v1[2], v1[3]);
;                     *(u32x4*)(rowp + bj * 128) = w; } }
	ds_read_b128 v[186:189], v191 offset:8704
	v_pk_add_f32 v[78:79], v[78:79], 0 op_sel_hi:[1,0]
	v_pk_add_f32 v[80:81], v[80:81], 0 op_sel_hi:[1,0]
	v_pk_mul_f32 v[78:79], v[78:79], v[240:241]
	v_pk_mul_f32 v[80:81], v[80:81], v[242:243]
	v_pk_add_f32 v[74:75], v[74:75], 0 op_sel_hi:[1,0]
	v_pk_add_f32 v[76:77], v[76:77], 0 op_sel_hi:[1,0]
	v_pk_mul_f32 v[74:75], v[74:75], v[244:245]
	v_pk_mul_f32 v[76:77], v[76:77], v[246:247]
	v_cvt_pk_bf16_f32 v178, v78, v79
	v_cvt_pk_bf16_f32 v179, v80, v81
	v_cvt_pk_bf16_f32 v180, v74, v75
	v_cvt_pk_bf16_f32 v181, v76, v77
	ds_write_b128 v190, v[178:181]
	s_waitcnt lgkmcnt(1)
	global_store_dwordx4 v[206:207], v[186:189], off offset:256 nt
	s_waitcnt lgkmcnt(0)
	s_barrier
	ds_read_b128 v[182:185], v191
	s_mov_b32 s24, 0x30000
	v_lshl_add_u64 v[206:207], v[204:205], 0, s[24:25]
	v_pk_add_f32 v[70:71], v[70:71], 0 op_sel_hi:[1,0]
	v_pk_add_f32 v[72:73], v[72:73], 0 op_sel_hi:[1,0]
	v_pk_mul_f32 v[70:71], v[70:71], v[248:249]
	v_pk_mul_f32 v[72:73], v[72:73], v[250:251]
	v_pk_add_f32 v[66:67], v[66:67], 0 op_sel_hi:[1,0]
	v_pk_add_f32 v[68:69], v[68:69], 0 op_sel_hi:[1,0]
	v_pk_mul_f32 v[66:67], v[66:67], v[252:253]
	v_pk_mul_f32 v[68:69], v[68:69], v[254:255]
	v_cvt_pk_bf16_f32 v178, v70, v71
	v_cvt_pk_bf16_f32 v179, v72, v73
	v_cvt_pk_bf16_f32 v180, v66, v67
	v_cvt_pk_bf16_f32 v181, v68, v69
	ds_write_b128 v190, v[178:181] offset:8704
	s_waitcnt lgkmcnt(1)
	global_store_dwordx4 v[206:207], v[182:185], off nt
	s_waitcnt lgkmcnt(0)
	s_barrier
	ds_read_b128 v[186:189], v191 offset:8704
	v_pk_add_f32 v[60:61], v[60:61], 0 op_sel_hi:[1,0]
	v_pk_add_f32 v[62:63], v[62:63], 0 op_sel_hi:[1,0]
	v_pk_mul_f32 v[60:61], v[60:61], v[240:241]
	v_pk_mul_f32 v[62:63], v[62:63], v[242:243]
	v_pk_add_f32 v[56:57], v[56:57], 0 op_sel_hi:[1,0]
	v_pk_add_f32 v[58:59], v[58:59], 0 op_sel_hi:[1,0]
	v_pk_mul_f32 v[56:57], v[56:57], v[244:245]
	v_pk_mul_f32 v[58:59], v[58:59], v[246:247]
	v_cvt_pk_bf16_f32 v178, v60, v61
	v_cvt_pk_bf16_f32 v179, v62, v63
	v_cvt_pk_bf16_f32 v180, v56, v57
	v_cvt_pk_bf16_f32 v181, v58, v59
	ds_write_b128 v190, v[178:181]
	s_waitcnt lgkmcnt(1)
	global_store_dwordx4 v[206:207], v[186:189], off offset:256 nt
	s_waitcnt lgkmcnt(0)
	s_barrier
	ds_read_b128 v[182:185], v191
	s_mov_b32 s24, 0x80000
	v_lshl_add_u64 v[206:207], v[204:205], 0, s[24:25]
	v_pk_add_f32 v[52:53], v[52:53], 0 op_sel_hi:[1,0]
	v_pk_add_f32 v[54:55], v[54:55], 0 op_sel_hi:[1,0]
	v_pk_mul_f32 v[52:53], v[52:53], v[248:249]
	v_pk_mul_f32 v[54:55], v[54:55], v[250:251]
	v_pk_add_f32 v[48:49], v[48:49], 0 op_sel_hi:[1,0]
	v_pk_add_f32 v[50:51], v[50:51], 0 op_sel_hi:[1,0]
	v_pk_mul_f32 v[48:49], v[48:49], v[252:253]
	v_pk_mul_f32 v[50:51], v[50:51], v[254:255]
	v_cvt_pk_bf16_f32 v178, v52, v53
	v_cvt_pk_bf16_f32 v179, v54, v55
	v_cvt_pk_bf16_f32 v180, v48, v49
	v_cvt_pk_bf16_f32 v181, v50, v51
	ds_write_b128 v190, v[178:181] offset:8704
	s_waitcnt lgkmcnt(1)
	global_store_dwordx4 v[206:207], v[182:185], off nt
	s_waitcnt lgkmcnt(0)
	s_barrier
	ds_read_b128 v[186:189], v191 offset:8704
	v_pk_add_f32 v[44:45], v[44:45], 0 op_sel_hi:[1,0]
	v_pk_add_f32 v[46:47], v[46:47], 0 op_sel_hi:[1,0]
	v_pk_mul_f32 v[44:45], v[44:45], v[240:241]
	v_pk_mul_f32 v[46:47], v[46:47], v[242:243]
	v_pk_add_f32 v[40:41], v[40:41], 0 op_sel_hi:[1,0]
	v_pk_add_f32 v[42:43], v[42:43], 0 op_sel_hi:[1,0]
	v_pk_mul_f32 v[40:41], v[40:41], v[244:245]
	v_pk_mul_f32 v[42:43], v[42:43], v[246:247]
	v_cvt_pk_bf16_f32 v178, v44, v45
	v_cvt_pk_bf16_f32 v179, v46, v47
	v_cvt_pk_bf16_f32 v180, v40, v41
	v_cvt_pk_bf16_f32 v181, v42, v43
	ds_write_b128 v190, v[178:181]
	s_waitcnt lgkmcnt(1)
	global_store_dwordx4 v[206:207], v[186:189], off offset:256 nt
	s_waitcnt lgkmcnt(0)
	s_barrier
; __device__ __forceinline__ unsigned pk2(float lo, float hi) { const v2f_t f = {lo, hi}; const v2bf_t b = __builtin_convertvector(f, v2bf_t); return __builtin_bit_cast(unsigned, b); }
;     __device__ __forceinline__ void operator()(const f32x4 (&acc)[2][2][4][2], const Unit& u, int wr, int wc, int fr, int fq) const {
;     ...
;         for (int ai = 0; ai < 2; ++ai)
; #pragma unroll
;             for (int m = 0; m < 4; ++m) { bf16_t* rowp = delta + (size_t)(row0 + ai * 128 + m * 16) * D + col0;
; #pragma unroll
;                 for (int bj = 0; bj < 2; ++bj) { const f32x4 v0 = gv[bj][0] * (acc[ai][bj][m][0] + bv[bj][0]), v1 = gv[bj][1] * (acc[ai][bj][m][1] + bv[bj][1]);
;                     u32x4 w; w.x = pk2(v0[0], v0[1]); w.y = pk2(v0[2], v0[3]); w.z = pk2(v1[0], v1[1]); w.w = pk2(v1[2], v1[3]);
;                     *(u32x4*)(rowp + bj * 128) = w; } }
	ds_read_b128 v[182:185], v191
	s_mov_b32 s24, 0x90000
	v_lshl_add_u64 v[206:207], v[204:205], 0, s[24:25]
	v_pk_add_f32 v[36:37], v[36:37], 0 op_sel_hi:[1,0]
	v_pk_add_f32 v[38:39], v[38:39], 0 op_sel_hi:[1,0]
	v_pk_mul_f32 v[36:37], v[36:37], v[248:249]
	v_pk_mul_f32 v[38:39], v[38:39], v[250:251]
	v_pk_add_f32 v[32:33], v[32:33], 0 op_sel_hi:[1,0]
	v_pk_add_f32 v[34:35], v[34:35], 0 op_sel_hi:[1,0]
	v_pk_mul_f32 v[32:33], v[32:33], v[252:253]
	v_pk_mul_f32 v[34:35], v[34:35], v[254:255]
	v_cvt_pk_bf16_f32 v178, v36, v37
	v_cvt_pk_bf16_f32 v179, v38, v39
	v_cvt_pk_bf16_f32 v180, v32, v33
	v_cvt_pk_bf16_f32 v181, v34, v35
	ds_write_b128 v190, v[178:181] offset:8704
	s_waitcnt lgkmcnt(1)
	global_store_dwordx4 v[206:207], v[182:185], off nt
	s_waitcnt lgkmcnt(0)
	s_barrier
	ds_read_b128 v[186:189], v191 offset:8704
	v_pk_add_f32 v[28:29], v[28:29], 0 op_sel_hi:[1,0]
	v_pk_add_f32 v[30:31], v[30:31], 0 op_sel_hi:[1,0]
	v_pk_mul_f32 v[28:29], v[28:29], v[240:241]
	v_pk_mul_f32 v[30:31], v[30:31], v[242:243]
	v_pk_add_f32 v[24:25], v[24:25], 0 op_sel_hi:[1,0]
	v_pk_add_f32 v[26:27], v[26:27], 0 op_sel_hi:[1,0]
	v_pk_mul_f32 v[24:25], v[24:25], v[244:245]
	v_pk_mul_f32 v[26:27], v[26:27], v[246:247]
	v_cvt_pk_bf16_f32 v178, v28, v29
	v_cvt_pk_bf16_f32 v179, v30, v31
	v_cvt_pk_bf16_f32 v180, v24, v25
	v_cvt_pk_bf16_f32 v181, v26, v27
	ds_write_b128 v190, v[178:181]
	s_waitcnt lgkmcnt(1)
	global_store_dwordx4 v[206:207], v[186:189], off offset:256 nt
	s_waitcnt lgkmcnt(0)
	s_barrier
	ds_read_b128 v[182:185], v191
	s_mov_b32 s24, 0xa0000
	v_lshl_add_u64 v[206:207], v[204:205], 0, s[24:25]
	v_pk_add_f32 v[20:21], v[20:21], 0 op_sel_hi:[1,0]
	v_pk_add_f32 v[22:23], v[22:23], 0 op_sel_hi:[1,0]
	v_pk_mul_f32 v[20:21], v[20:21], v[248:249]
	v_pk_mul_f32 v[22:23], v[22:23], v[250:251]
	v_pk_add_f32 v[16:17], v[16:17], 0 op_sel_hi:[1,0]
	v_pk_add_f32 v[18:19], v[18:19], 0 op_sel_hi:[1,0]
	v_pk_mul_f32 v[16:17], v[16:17], v[252:253]
	v_pk_mul_f32 v[18:19], v[18:19], v[254:255]
	v_cvt_pk_bf16_f32 v178, v20, v21
	v_cvt_pk_bf16_f32 v179, v22, v23
	v_cvt_pk_bf16_f32 v180, v16, v17
	v_cvt_pk_bf16_f32 v181, v18, v19
	ds_write_b128 v190, v[178:181] offset:8704
	s_waitcnt lgkmcnt(1)
	global_store_dwordx4 v[206:207], v[182:185], off nt
	s_waitcnt lgkmcnt(0)
	s_barrier
	ds_read_b128 v[186:189], v191 offset:8704
	v_pk_add_f32 v[12:13], v[12:13], 0 op_sel_hi:[1,0]
	v_pk_add_f32 v[14:15], v[14:15], 0 op_sel_hi:[1,0]
	v_pk_mul_f32 v[12:13], v[12:13], v[240:241]
	v_pk_mul_f32 v[14:15], v[14:15], v[242:243]
	v_pk_add_f32 v[8:9], v[8:9], 0 op_sel_hi:[1,0]
	v_pk_add_f32 v[10:11], v[10:11], 0 op_sel_hi:[1,0]
	v_pk_mul_f32 v[8:9], v[8:9], v[244:245]
	v_pk_mul_f32 v[10:11], v[10:11], v[246:247]
	v_cvt_pk_bf16_f32 v178, v12, v13
	v_cvt_pk_bf16_f32 v179, v14, v15
	v_cvt_pk_bf16_f32 v180, v8, v9
	v_cvt_pk_bf16_f32 v181, v10, v11
	ds_write_b128 v190, v[178:181]
	s_waitcnt lgkmcnt(1)
	global_store_dwordx4 v[206:207], v[186:189], off offset:256 nt
	s_waitcnt lgkmcnt(0)
	s_barrier
	ds_read_b128 v[182:185], v191
	s_mov_b32 s24, 0xb0000
	v_lshl_add_u64 v[206:207], v[204:205], 0, s[24:25]
	v_pk_add_f32 v[4:5], v[4:5], 0 op_sel_hi:[1,0]
	v_pk_add_f32 v[6:7], v[6:7], 0 op_sel_hi:[1,0]
	v_pk_mul_f32 v[4:5], v[4:5], v[248:249]
	v_pk_mul_f32 v[6:7], v[6:7], v[250:251]
	v_pk_add_f32 v[0:1], v[0:1], 0 op_sel_hi:[1,0]
	v_pk_add_f32 v[2:3], v[2:3], 0 op_sel_hi:[1,0]
	v_pk_mul_f32 v[0:1], v[0:1], v[252:253]
	v_pk_mul_f32 v[2:3], v[2:3], v[254:255]
	v_cvt_pk_bf16_f32 v178, v4, v5
	v_cvt_pk_bf16_f32 v179, v6, v7
	v_cvt_pk_bf16_f32 v180, v0, v1
	v_cvt_pk_bf16_f32 v181, v2, v3
	ds_write_b128 v190, v[178:181] offset:8704
	s_waitcnt lgkmcnt(1)
	global_store_dwordx4 v[206:207], v[182:185], off nt
	s_waitcnt lgkmcnt(0)
	s_barrier
	ds_read_b128 v[186:189], v191 offset:8704
	s_waitcnt lgkmcnt(0)
	global_store_dwordx4 v[206:207], v[186:189], off offset:256 nt
	s_mov_b64 s[24:25], 0

; __device__ __forceinline__ unsigned pk2(float lo, float hi) { const v2f_t f = {lo, hi}; const v2bf_t b = __builtin_convertvector(f, v2bf_t); return __builtin_bit_cast(unsigned, b); }
;     __device__ __forceinline__ void operator()(const f32x4 (&acc)[2][2][4][2], const Unit& u, int wr, int wc, int fr, int fq) const {
;     ...
;             for (int n = 0; n < 2; ++n) { gv[bj][n] = *(const f32x4*)(gp + bj * 128 + 4 * n); bv[bj][n] = bias ? *(const f32x4*)(bias + col0 + bj * 128 + 4 * n) : (f32x4){0.f, 0.f, 0.f, 0.f}; }
; #pragma unroll
;         for (int ai = 0; ai < 2; ++ai)
; #pragma unroll
;             for (int m = 0; m < 4; ++m) { bf16_t* rowp = delta + (size_t)(row0 + ai * 128 + m * 16) * D + col0;
; #pragma unroll
;                 for (int bj = 0; bj < 2; ++bj) { const f32x4 v0 = gv[bj][0] * (acc[ai][bj][m][0] + bv[bj][0]), v1 = gv[bj][1] * (acc[ai][bj][m][1] + bv[bj][1]);
;                     u32x4 w; w.x = pk2(v0[0], v0[1]); w.y = pk2(v0[2], v0[3]); w.z = pk2(v1[0], v1[1]); w.w = pk2(v1[2], v1[3]);
;                     *(u32x4*)(rowp + bj * 128) = w; } }
.LBB0_973:
	v_and_b32_e32 v183, 15, v194
	v_bfe_u32 v184, v194, 6, 2
	v_bfe_u32 v185, v194, 4, 2
	v_bfe_u32 v218, v194, 8, 1
	v_lshlrev_b32_e32 v218, 4, v218
	v_add_u32_e32 v218, v218, v183
	v_mul_u32_u24_e32 v212, 0x110, v218
	v_lshl_add_u32 v212, v184, 6, v212
	v_lshl_add_u32 v212, v185, 4, v212
	v_add_u32_e32 v212, 0x23410, v212
	v_lshrrev_b32_e32 v218, 6, v194
	v_lshl_add_u32 v218, v218, 2, v185
	v_mul_u32_u24_e32 v213, 0x110, v218
	v_lshl_add_u32 v213, v183, 4, v213
	v_add_u32_e32 v213, 0x23410, v213
	v_sub_u32_e32 v218, v182, v183
	v_lshl_add_u32 v218, v184, 2, v218
	v_add_u32_e32 v218, v218, v185
	v_lshlrev_b32_e32 v218, 12, v218
	v_and_b32_e32 v219, 0xffffff00, v180
	v_lshlrev_b32_e32 v219, 1, v219
	v_lshl_add_u32 v219, v183, 4, v219
	v_add_u32_e32 v218, v218, v219
	v_mov_b32_e32 v219, 0
	v_lshl_add_u64 v[214:215], s[2:3], 0, v[218:219]
	s_mov_b32 s11, 0
	s_mov_b64 s[20:21], 0
	s_waitcnt vmcnt(0)
	v_pk_add_f32 v[126:127], v[126:127], v[138:139]
	v_pk_add_f32 v[128:129], v[128:129], v[140:141]
	v_pk_mul_f32 v[126:127], v[134:135], v[126:127]
	v_pk_mul_f32 v[128:129], v[136:137], v[128:129]
	v_pk_add_f32 v[122:123], v[122:123], v[130:131]
	v_pk_add_f32 v[124:125], v[124:125], v[132:133]
	v_pk_mul_f32 v[122:123], v[142:143], v[122:123]
	v_pk_mul_f32 v[124:125], v[144:145], v[124:125]
	v_cvt_pk_bf16_f32 v190, v126, v127
	v_cvt_pk_bf16_f32 v191, v128, v129
	v_cvt_pk_bf16_f32 v192, v122, v123
	v_cvt_pk_bf16_f32 v193, v124, v125
	ds_write_b128 v212, v[190:193]
	s_waitcnt lgkmcnt(0)
	s_barrier
	ds_read_b128 v[204:207], v213
	s_mov_b32 s10, 0x0
	v_lshl_add_u64 v[216:217], v[214:215], 0, s[10:11]
	v_pk_add_f32 v[118:119], v[118:119], v[154:155]
	v_pk_add_f32 v[120:121], v[120:121], v[156:157]
	v_pk_mul_f32 v[118:119], v[150:151], v[118:119]
	v_pk_mul_f32 v[120:121], v[152:153], v[120:121]
	v_pk_add_f32 v[114:115], v[114:115], v[146:147]
	v_pk_add_f32 v[116:117], v[116:117], v[148:149]
	v_pk_mul_f32 v[114:115], v[158:159], v[114:115]
	v_pk_mul_f32 v[116:117], v[160:161], v[116:117]
	v_cvt_pk_bf16_f32 v190, v118, v119
	v_cvt_pk_bf16_f32 v191, v120, v121
	v_cvt_pk_bf16_f32 v192, v114, v115
	v_cvt_pk_bf16_f32 v193, v116, v117
	ds_write_b128 v212, v[190:193] offset:8704
	s_waitcnt lgkmcnt(1)
	global_store_dwordx4 v[216:217], v[204:207], off nt
	s_waitcnt lgkmcnt(0)
	s_barrier
	ds_read_b128 v[208:211], v213 offset:8704
	v_pk_add_f32 v[110:111], v[110:111], v[138:139]
	v_pk_add_f32 v[112:113], v[112:113], v[140:141]
	v_pk_mul_f32 v[110:111], v[134:135], v[110:111]
	v_pk_mul_f32 v[112:113], v[136:137], v[112:113]
	v_pk_add_f32 v[106:107], v[106:107], v[130:131]
	v_pk_add_f32 v[108:109], v[108:109], v[132:133]
	v_pk_mul_f32 v[106:107], v[142:143], v[106:107]
	v_pk_mul_f32 v[108:109], v[144:145], v[108:109]
	v_cvt_pk_bf16_f32 v190, v110, v111
	v_cvt_pk_bf16_f32 v191, v112, v113
	v_cvt_pk_bf16_f32 v192, v106, v107
	v_cvt_pk_bf16_f32 v193, v108, v109
	ds_write_b128 v212, v[190:193]
	s_waitcnt lgkmcnt(1)
	global_store_dwordx4 v[216:217], v[208:211], off offset:256 nt
	s_waitcnt lgkmcnt(0)
	s_barrier
	ds_read_b128 v[204:207], v213
	s_mov_b32 s10, 0x10000
	v_lshl_add_u64 v[216:217], v[214:215], 0, s[10:11]
	v_pk_add_f32 v[102:103], v[102:103], v[154:155]
	v_pk_add_f32 v[104:105], v[104:105], v[156:157]
	v_pk_mul_f32 v[102:103], v[150:151], v[102:103]
	v_pk_mul_f32 v[104:105], v[152:153], v[104:105]
	v_pk_add_f32 v[98:99], v[98:99], v[146:147]
	v_pk_add_f32 v[100:101], v[100:101], v[148:149]
	v_pk_mul_f32 v[98:99], v[158:159], v[98:99]
	v_pk_mul_f32 v[100:101], v[160:161], v[100:101]
	v_cvt_pk_bf16_f32 v190, v102, v103
	v_cvt_pk_bf16_f32 v191, v104, v105
	v_cvt_pk_bf16_f32 v192, v98, v99
	v_cvt_pk_bf16_f32 v193, v100, v101
	ds_write_b128 v212, v[190:193] offset:8704
	s_waitcnt lgkmcnt(1)
	global_store_dwordx4 v[216:217], v[204:207], off nt
	s_waitcnt lgkmcnt(0)
	s_barrier
	ds_read_b128 v[208:211], v213 offset:8704
	v_pk_add_f32 v[94:95], v[94:95], v[138:139]
	v_pk_add_f32 v[96:97], v[96:97], v[140:141]
	v_pk_mul_f32 v[94:95], v[134:135], v[94:95]
	v_pk_mul_f32 v[96:97], v[136:137], v[96:97]
	v_pk_add_f32 v[90:91], v[90:91], v[130:131]
	v_pk_add_f32 v[92:93], v[92:93], v[132:133]
	v_pk_mul_f32 v[90:91], v[142:143], v[90:91]
	v_pk_mul_f32 v[92:93], v[144:145], v[92:93]
	v_cvt_pk_bf16_f32 v190, v94, v95
	v_cvt_pk_bf16_f32 v191, v96, v97
	v_cvt_pk_bf16_f32 v192, v90, v91
	v_cvt_pk_bf16_f32 v193, v92, v93
	ds_write_b128 v212, v[190:193]
	s_waitcnt lgkmcnt(1)
	global_store_dwordx4 v[216:217], v[208:211], off offset:256 nt
	s_waitcnt lgkmcnt(0)
	s_barrier
	ds_read_b128 v[204:207], v213
	s_mov_b32 s10, 0x20000
	v_lshl_add_u64 v[216:217], v[214:215], 0, s[10:11]
	v_pk_add_f32 v[86:87], v[86:87], v[154:155]
	v_pk_add_f32 v[88:89], v[88:89], v[156:157]
	v_pk_mul_f32 v[86:87], v[150:151], v[86:87]
	v_pk_mul_f32 v[88:89], v[152:153], v[88:89]
	v_pk_add_f32 v[82:83], v[82:83], v[146:147]
	v_pk_add_f32 v[84:85], v[84:85], v[148:149]
	v_pk_mul_f32 v[82:83], v[158:159], v[82:83]
	v_pk_mul_f32 v[84:85], v[160:161], v[84:85]
	v_cvt_pk_bf16_f32 v190, v86, v87
	v_cvt_pk_bf16_f32 v191, v88, v89
	v_cvt_pk_bf16_f32 v192, v82, v83
	v_cvt_pk_bf16_f32 v193, v84, v85
	ds_write_b128 v212, v[190:193] offset:8704
	s_waitcnt lgkmcnt(1)
	global_store_dwordx4 v[216:217], v[204:207], off nt
	s_waitcnt lgkmcnt(0)
	s_barrier
	ds_read_b128 v[208:211], v213 offset:8704
	v_pk_add_f32 v[78:79], v[78:79], v[138:139]
	v_pk_add_f32 v[80:81], v[80:81], v[140:141]
	v_pk_mul_f32 v[78:79], v[134:135], v[78:79]
	v_pk_mul_f32 v[80:81], v[136:137], v[80:81]
	v_pk_add_f32 v[74:75], v[74:75], v[130:131]
	v_pk_add_f32 v[76:77], v[76:77], v[132:133]
	v_pk_mul_f32 v[74:75], v[142:143], v[74:75]
	v_pk_mul_f32 v[76:77], v[144:145], v[76:77]
	v_cvt_pk_bf16_f32 v190, v78, v79
	v_cvt_pk_bf16_f32 v191, v80, v81
	v_cvt_pk_bf16_f32 v192, v74, v75
	v_cvt_pk_bf16_f32 v193, v76, v77
	ds_write_b128 v212, v[190:193]
	s_waitcnt lgkmcnt(1)
	global_store_dwordx4 v[216:217], v[208:211], off offset:256 nt
	s_waitcnt lgkmcnt(0)
	s_barrier
; __device__ __forceinline__ unsigned pk2(float lo, float hi) { const v2f_t f = {lo, hi}; const v2bf_t b = __builtin_convertvector(f, v2bf_t); return __builtin_bit_cast(unsigned, b); }
;     __device__ __forceinline__ void operator()(const f32x4 (&acc)[2][2][4][2], const Unit& u, int wr, int wc, int fr, int fq) const {
;     ...
;         for (int ai = 0; ai < 2; ++ai)
; #pragma unroll
;             for (int m = 0; m < 4; ++m) { bf16_t* rowp = delta + (size_t)(row0 + ai * 128 + m * 16) * D + col0;
; #pragma unroll
;                 for (int bj = 0; bj < 2; ++bj) { const f32x4 v0 = gv[bj][0] * (acc[ai][bj][m][0] + bv[bj][0]), v1 = gv[bj][1] * (acc[ai][bj][m][1] + bv[bj][1]);
;                     u32x4 w; w.x = pk2(v0[0], v0[1]); w.y = pk2(v0[2], v0[3]); w.z = pk2(v1[0], v1[1]); w.w = pk2(v1[2], v1[3]);
;                     *(u32x4*)(rowp + bj * 128) = w; } }
	ds_read_b128 v[204:207], v213
	s_mov_b32 s10, 0x30000
	v_lshl_add_u64 v[216:217], v[214:215], 0, s[10:11]
	v_pk_add_f32 v[70:71], v[70:71], v[154:155]
	v_pk_add_f32 v[72:73], v[72:73], v[156:157]
	v_pk_mul_f32 v[70:71], v[150:151], v[70:71]
	v_pk_mul_f32 v[72:73], v[152:153], v[72:73]
	v_pk_add_f32 v[66:67], v[66:67], v[146:147]
	v_pk_add_f32 v[68:69], v[68:69], v[148:149]
	v_pk_mul_f32 v[66:67], v[158:159], v[66:67]
	v_pk_mul_f32 v[68:69], v[160:161], v[68:69]
	v_cvt_pk_bf16_f32 v190, v70, v71
	v_cvt_pk_bf16_f32 v191, v72, v73
	v_cvt_pk_bf16_f32 v192, v66, v67
	v_cvt_pk_bf16_f32 v193, v68, v69
	ds_write_b128 v212, v[190:193] offset:8704
	s_waitcnt lgkmcnt(1)
	global_store_dwordx4 v[216:217], v[204:207], off nt
	s_waitcnt lgkmcnt(0)
	s_barrier
	ds_read_b128 v[208:211], v213 offset:8704
	v_pk_add_f32 v[60:61], v[60:61], v[138:139]
	v_pk_add_f32 v[62:63], v[62:63], v[140:141]
	v_pk_mul_f32 v[60:61], v[134:135], v[60:61]
	v_pk_mul_f32 v[62:63], v[136:137], v[62:63]
	v_pk_add_f32 v[56:57], v[56:57], v[130:131]
	v_pk_add_f32 v[58:59], v[58:59], v[132:133]
	v_pk_mul_f32 v[56:57], v[142:143], v[56:57]
	v_pk_mul_f32 v[58:59], v[144:145], v[58:59]
	v_cvt_pk_bf16_f32 v190, v60, v61
	v_cvt_pk_bf16_f32 v191, v62, v63
	v_cvt_pk_bf16_f32 v192, v56, v57
	v_cvt_pk_bf16_f32 v193, v58, v59
	ds_write_b128 v212, v[190:193]
	s_waitcnt lgkmcnt(1)
	global_store_dwordx4 v[216:217], v[208:211], off offset:256 nt
	s_waitcnt lgkmcnt(0)
	s_barrier
	ds_read_b128 v[204:207], v213
	s_mov_b32 s10, 0x80000
	v_lshl_add_u64 v[216:217], v[214:215], 0, s[10:11]
	v_pk_add_f32 v[52:53], v[52:53], v[154:155]
	v_pk_add_f32 v[54:55], v[54:55], v[156:157]
	v_pk_mul_f32 v[52:53], v[150:151], v[52:53]
	v_pk_mul_f32 v[54:55], v[152:153], v[54:55]
	v_pk_add_f32 v[48:49], v[48:49], v[146:147]
	v_pk_add_f32 v[50:51], v[50:51], v[148:149]
	v_pk_mul_f32 v[48:49], v[158:159], v[48:49]
	v_pk_mul_f32 v[50:51], v[160:161], v[50:51]
	v_cvt_pk_bf16_f32 v190, v52, v53
	v_cvt_pk_bf16_f32 v191, v54, v55
	v_cvt_pk_bf16_f32 v192, v48, v49
	v_cvt_pk_bf16_f32 v193, v50, v51
	ds_write_b128 v212, v[190:193] offset:8704
	s_waitcnt lgkmcnt(1)
	global_store_dwordx4 v[216:217], v[204:207], off nt
	s_waitcnt lgkmcnt(0)
	s_barrier
	ds_read_b128 v[208:211], v213 offset:8704
	v_pk_add_f32 v[44:45], v[44:45], v[138:139]
	v_pk_add_f32 v[46:47], v[46:47], v[140:141]
	v_pk_mul_f32 v[44:45], v[134:135], v[44:45]
	v_pk_mul_f32 v[46:47], v[136:137], v[46:47]
	v_pk_add_f32 v[40:41], v[40:41], v[130:131]
	v_pk_add_f32 v[42:43], v[42:43], v[132:133]
	v_pk_mul_f32 v[40:41], v[142:143], v[40:41]
	v_pk_mul_f32 v[42:43], v[144:145], v[42:43]
	v_cvt_pk_bf16_f32 v190, v44, v45
	v_cvt_pk_bf16_f32 v191, v46, v47
	v_cvt_pk_bf16_f32 v192, v40, v41
	v_cvt_pk_bf16_f32 v193, v42, v43
	ds_write_b128 v212, v[190:193]
	s_waitcnt lgkmcnt(1)
	global_store_dwordx4 v[216:217], v[208:211], off offset:256 nt
	s_waitcnt lgkmcnt(0)
	s_barrier
	ds_read_b128 v[204:207], v213
	s_mov_b32 s10, 0x90000
	v_lshl_add_u64 v[216:217], v[214:215], 0, s[10:11]
	v_pk_add_f32 v[36:37], v[36:37], v[154:155]
	v_pk_add_f32 v[38:39], v[38:39], v[156:157]
	v_pk_mul_f32 v[36:37], v[150:151], v[36:37]
	v_pk_mul_f32 v[38:39], v[152:153], v[38:39]
	v_pk_add_f32 v[32:33], v[32:33], v[146:147]
	v_pk_add_f32 v[34:35], v[34:35], v[148:149]
	v_pk_mul_f32 v[32:33], v[158:159], v[32:33]
	v_pk_mul_f32 v[34:35], v[160:161], v[34:35]
	v_cvt_pk_bf16_f32 v190, v36, v37
	v_cvt_pk_bf16_f32 v191, v38, v39
	v_cvt_pk_bf16_f32 v192, v32, v33
	v_cvt_pk_bf16_f32 v193, v34, v35
	ds_write_b128 v212, v[190:193] offset:8704
	s_waitcnt lgkmcnt(1)
	global_store_dwordx4 v[216:217], v[204:207], off nt
	s_waitcnt lgkmcnt(0)
	s_barrier
	ds_read_b128 v[208:211], v213 offset:8704
	v_pk_add_f32 v[28:29], v[28:29], v[138:139]
	v_pk_add_f32 v[30:31], v[30:31], v[140:141]
	v_pk_mul_f32 v[28:29], v[134:135], v[28:29]
	v_pk_mul_f32 v[30:31], v[136:137], v[30:31]
	v_pk_add_f32 v[24:25], v[24:25], v[130:131]
	v_pk_add_f32 v[26:27], v[26:27], v[132:133]
	v_pk_mul_f32 v[24:25], v[142:143], v[24:25]
	v_pk_mul_f32 v[26:27], v[144:145], v[26:27]
	v_cvt_pk_bf16_f32 v190, v28, v29
	v_cvt_pk_bf16_f32 v191, v30, v31
	v_cvt_pk_bf16_f32 v192, v24, v25
	v_cvt_pk_bf16_f32 v193, v26, v27
	ds_write_b128 v212, v[190:193]
	s_waitcnt lgkmcnt(1)
	global_store_dwordx4 v[216:217], v[208:211], off offset:256 nt
	s_waitcnt lgkmcnt(0)
	s_barrier
	ds_read_b128 v[204:207], v213
	s_mov_b32 s10, 0xa0000
	v_lshl_add_u64 v[216:217], v[214:215], 0, s[10:11]
	v_pk_add_f32 v[20:21], v[20:21], v[154:155]
	v_pk_add_f32 v[22:23], v[22:23], v[156:157]
	v_pk_mul_f32 v[20:21], v[150:151], v[20:21]
	v_pk_mul_f32 v[22:23], v[152:153], v[22:23]
	v_pk_add_f32 v[16:17], v[16:17], v[146:147]
	v_pk_add_f32 v[18:19], v[18:19], v[148:149]
	v_pk_mul_f32 v[16:17], v[158:159], v[16:17]
	v_pk_mul_f32 v[18:19], v[160:161], v[18:19]
	v_cvt_pk_bf16_f32 v190, v20, v21
	v_cvt_pk_bf16_f32 v191, v22, v23
	v_cvt_pk_bf16_f32 v192, v16, v17
	v_cvt_pk_bf16_f32 v193, v18, v19
	ds_write_b128 v212, v[190:193] offset:8704
	s_waitcnt lgkmcnt(1)
	global_store_dwordx4 v[216:217], v[204:207], off nt
	s_waitcnt lgkmcnt(0)
	s_barrier
	ds_read_b128 v[208:211], v213 offset:8704
	v_pk_add_f32 v[12:13], v[12:13], v[138:139]
	v_pk_add_f32 v[14:15], v[14:15], v[140:141]
	v_pk_mul_f32 v[12:13], v[134:135], v[12:13]
	v_pk_mul_f32 v[14:15], v[136:137], v[14:15]
	v_pk_add_f32 v[8:9], v[8:9], v[130:131]
	v_pk_add_f32 v[10:11], v[10:11], v[132:133]
	v_pk_mul_f32 v[8:9], v[142:143], v[8:9]
	v_pk_mul_f32 v[10:11], v[144:145], v[10:11]
	v_cvt_pk_bf16_f32 v190, v12, v13
	v_cvt_pk_bf16_f32 v191, v14, v15
	v_cvt_pk_bf16_f32 v192, v8, v9
	v_cvt_pk_bf16_f32 v193, v10, v11
	ds_write_b128 v212, v[190:193]
	s_waitcnt lgkmcnt(1)
	global_store_dwordx4 v[216:217], v[208:211], off offset:256 nt
	s_waitcnt lgkmcnt(0)
	s_barrier
	ds_read_b128 v[204:207], v213
	s_mov_b32 s10, 0xb0000
	v_lshl_add_u64 v[216:217], v[214:215], 0, s[10:11]
	v_pk_add_f32 v[4:5], v[4:5], v[154:155]
	v_pk_add_f32 v[6:7], v[6:7], v[156:157]
	v_pk_mul_f32 v[4:5], v[150:151], v[4:5]
	v_pk_mul_f32 v[6:7], v[152:153], v[6:7]
	v_pk_add_f32 v[0:1], v[0:1], v[146:147]
	v_pk_add_f32 v[2:3], v[2:3], v[148:149]
	v_pk_mul_f32 v[0:1], v[158:159], v[0:1]
	v_pk_mul_f32 v[2:3], v[160:161], v[2:3]
	v_cvt_pk_bf16_f32 v190, v4, v5
	v_cvt_pk_bf16_f32 v191, v6, v7
	v_cvt_pk_bf16_f32 v192, v0, v1
	v_cvt_pk_bf16_f32 v193, v2, v3
	ds_write_b128 v212, v[190:193] offset:8704
	s_waitcnt lgkmcnt(1)
	global_store_dwordx4 v[216:217], v[204:207], off nt
	s_waitcnt lgkmcnt(0)
	s_barrier
	ds_read_b128 v[208:211], v213 offset:8704
	s_waitcnt lgkmcnt(0)
	global_store_dwordx4 v[216:217], v[208:211], off offset:256 nt
